# combo + post phase: next token's y/f rows prefetched at the start of the loop tail
# baseline (speedup 1.0000x reference)
.LBB0_278:
	s_andn2_b64 vcc, exec, s[2:3]
	s_cbranch_vccnz .LBB0_700
	s_lshl_b64 s[2:3], s[28:29], 9
	s_mul_hi_i32 s63, s28, 0x780
	s_mul_i32 s62, s28, 0x780
	s_cmp_lt_i32 s94, 3
	s_mov_b64 s[22:23], -1
	s_cbranch_scc1 .LBB0_497
	s_cmp_lt_i32 s94, 4
	s_cbranch_scc1 .LBB0_371
	s_cmp_gt_i32 s94, 4
	s_cbranch_scc0 .LBB0_298
	s_mov_b64 s[38:39], s[96:97]
	v_mov_b32_e32 v2, v1
	v_readlane_b32 s22, v245, 2
	v_ashrrev_i32_e32 v3, 6, v2
	s_nop 0
	v_add_u32_e32 v48, s22, v3
	s_mov_b32 s22, 0x8000
	v_cmp_gt_i32_e32 vcc, s22, v48
	s_and_saveexec_b64 s[22:23], vcc
	s_cbranch_execz .LBB0_297
	s_load_dwordx2 s[44:45], s[38:39], 0xf8
	s_load_dwordx2 s[46:47], s[38:39], 0xa0
	s_load_dwordx4 s[40:43], s[38:39], 0x90
	v_lshlrev_b32_e32 v2, 3, v2
	v_and_b32_e32 v2, 0x1f8, v2
	v_lshlrev_b32_e32 v4, 2, v2
	s_waitcnt lgkmcnt(0)
	s_add_u32 s30, s44, 0x6400000
	s_addc_u32 s31, s45, 0
	s_lshl_b64 s[48:49], s[2:3], 2
	s_add_u32 s42, s42, s48
	s_addc_u32 s43, s43, s49
	v_mov_b32_e32 v5, v34
	v_lshl_add_u64 v[50:51], s[42:43], 0, v[4:5]
	s_add_u32 s42, s46, s48
	s_addc_u32 s43, s47, s49
	s_add_u32 s40, s40, s48
	s_addc_u32 s41, s41, s49
	v_lshlrev_b32_e32 v6, 1, v2
	v_mov_b32_e32 v7, v34
	v_lshl_add_u64 v[54:55], s[40:41], 0, v[4:5]
	v_lshl_add_u64 v[6:7], s[44:45], 0, v[6:7]
	s_mov_b64 s[40:41], 0x1dc00000
	v_lshl_add_u64 v[52:53], s[42:43], 0, v[4:5]
	v_lshl_add_u64 v[56:57], v[6:7], 0, s[40:41]
	s_load_dwordx4 s[40:43], s[38:39], 0x48
	s_load_dword s24, s[72:73], 0x10
	s_lshl_b64 s[38:39], s[62:63], 2
	v_cmp_lt_i32_e32 vcc, v219, v218
	v_or_b32_e32 v6, 0x800, v2
	s_waitcnt lgkmcnt(0)
	s_add_u32 s42, s42, s38
	s_addc_u32 s43, s43, s39
	s_add_u32 s38, s40, s38
	s_addc_u32 s39, s41, s39
	s_lshr_b32 s24, s24, 16
	s_cmp_lg_u32 s24, 0
	v_cndmask_b32_e32 v3, v217, v219, vcc
	v_cmp_lt_i32_e32 vcc, v220, v218
	s_cselect_b64 s[40:41], -1, 0
	v_lshlrev_b32_e32 v35, 2, v3
	v_cndmask_b32_e32 v3, v217, v220, vcc
	v_cmp_lt_i32_e32 vcc, v221, v218
	s_cmp_lg_u64 s[40:41], 0
	v_lshlrev_b32_e32 v63, 2, v3
	v_cndmask_b32_e32 v3, v217, v221, vcc
	s_addc_u32 s24, s74, 0
	v_lshl_add_u64 v[58:59], s[38:39], 0, v[4:5]
	v_lshl_add_u64 v[60:61], s[42:43], 0, v[4:5]
	v_or_b32_e32 v4, 0x1000, v4
	v_lshlrev_b32_e32 v65, 2, v3
	s_lshl_b32 s24, s24, 3
	v_or_b32_e32 v62, 0xa00, v2
	v_or_b32_e32 v64, 0xc00, v2
	v_lshl_add_u64 v[66:67], s[38:39], 0, v[4:5]
	v_lshl_add_u64 v[68:69], s[42:43], 0, v[4:5]
	s_mov_b64 s[40:41], 0
	v_lshlrev_b32_e32 v70, 1, v2
	v_lshlrev_b32_e32 v72, 1, v6
	global_load_dwordx4 v[178:181], v[54:55], off offset:16
	global_load_dwordx4 v[182:185], v[54:55], off
	global_load_dwordx4 v[186:189], v[66:67], off offset:16
	global_load_dwordx4 v[190:193], v[66:67], off
	global_load_dwordx4 v[194:197], v[68:69], off offset:16
	global_load_dwordx4 v[198:201], v[68:69], off
	global_load_dwordx4 v[202:205], v[50:51], off offset:16
	global_load_dwordx4 v[206:209], v[50:51], off
	global_load_dwordx4 v[226:229], v[52:53], off offset:16
	global_load_dwordx4 v[230:233], v[52:53], off
	v_min_i32_e32 v246, 0x7fff, v48
	v_mov_b64_e32 v[242:243], s[30:31]
	v_mov_b32_e32 v248, v70
	v_mov_b32_e32 v249, 0
	v_mad_i64_i32 v[242:243], s[98:99], v246, s89, v[242:243]
	v_lshl_add_u64 v[242:243], v[242:243], 0, v[248:249]
	global_load_dwordx4 v[234:237], v[242:243], off
	global_load_dwordx4 v[238:241], v[242:243], off offset:3072
	s_waitcnt vmcnt(0)
	s_branch .LBB0_285
.LBB0_284:
	s_or_b64 exec, exec, s[42:43]
	s_waitcnt vmcnt(5)
	v_cvt_f32_f16_sdwa v117, v22 dst_sel:DWORD dst_unused:UNUSED_PAD src0_sel:WORD_1
	v_cvt_f32_f16_e32 v116, v22
	v_cvt_f32_f16_sdwa v135, v23 dst_sel:DWORD dst_unused:UNUSED_PAD src0_sel:WORD_1
	v_cvt_f32_f16_e32 v134, v23
	v_cvt_f32_f16_sdwa v23, v24 dst_sel:DWORD dst_unused:UNUSED_PAD src0_sel:WORD_1
	v_cvt_f32_f16_e32 v22, v24
	v_cvt_f32_f16_sdwa v139, v25 dst_sel:DWORD dst_unused:UNUSED_PAD src0_sel:WORD_1
	v_cvt_f32_f16_e32 v138, v25
	v_pk_add_f32 v[24:25], v[126:127], v[116:117] neg_lo:[0,1] neg_hi:[0,1]
	v_ashrrev_i32_e32 v49, 31, v48
	s_waitcnt vmcnt(3)
	v_pk_fma_f32 v[24:25], v[24:25], v[44:45], v[116:117]
	v_pk_add_f32 v[44:45], v[132:133], v[116:117] neg_lo:[0,1] neg_hi:[0,1]
	s_waitcnt vmcnt(1)
	v_pk_fma_f32 v[44:45], v[44:45], v[40:41], v[24:25]
	v_pk_add_f32 v[24:25], v[124:125], v[134:135] neg_lo:[0,1] neg_hi:[0,1]
	v_pk_add_f32 v[40:41], v[130:131], v[134:135] neg_lo:[0,1] neg_hi:[0,1]
	v_pk_fma_f32 v[24:25], v[24:25], v[46:47], v[134:135]
	s_nop 0
	v_pk_fma_f32 v[24:25], v[40:41], v[42:43], v[24:25]
	v_pk_add_f32 v[40:41], v[122:123], v[22:23] neg_lo:[0,1] neg_hi:[0,1]
	v_cvt_f32_f16_sdwa v43, v5 dst_sel:DWORD dst_unused:UNUSED_PAD src0_sel:WORD_1
	v_pk_fma_f32 v[30:31], v[40:41], v[30:31], v[22:23]
	v_pk_add_f32 v[22:23], v[128:129], v[22:23] neg_lo:[0,1] neg_hi:[0,1]
	s_waitcnt vmcnt(0)
	v_add_u32_e32 v247, s24, v48
	v_min_i32_e32 v246, 0x7fff, v247
	v_mov_b64_e32 v[242:243], s[30:31]
	v_mov_b32_e32 v248, v70
	v_mov_b32_e32 v249, 0
	v_mad_i64_i32 v[242:243], s[98:99], v246, s89, v[242:243]
	v_lshl_add_u64 v[242:243], v[242:243], 0, v[248:249]
	global_load_dwordx4 v[234:237], v[242:243], off
	global_load_dwordx4 v[238:241], v[242:243], off offset:3072
	v_cvt_f32_f16_sdwa v41, v27 dst_sel:DWORD dst_unused:UNUSED_PAD src0_sel:WORD_1
	v_pk_fma_f32 v[30:31], v[22:23], v[36:37], v[30:31]
	v_pk_add_f32 v[22:23], v[120:121], v[138:139] neg_lo:[0,1] neg_hi:[0,1]
	v_cvt_f32_f16_e32 v40, v27
	v_pk_fma_f32 v[22:23], v[22:23], v[32:33], v[138:139]
	v_pk_add_f32 v[32:33], v[118:119], v[138:139] neg_lo:[0,1] neg_hi:[0,1]
	v_cvt_f32_f16_sdwa v27, v2 dst_sel:DWORD dst_unused:UNUSED_PAD src0_sel:WORD_1
	v_pk_fma_f32 v[32:33], v[32:33], v[38:39], v[22:23]
	v_cvt_f32_f16_sdwa v23, v26 dst_sel:DWORD dst_unused:UNUSED_PAD src0_sel:WORD_1
	v_cvt_f32_f16_e32 v22, v26
	v_cvt_f32_f16_e32 v26, v2
	v_cvt_f32_f16_sdwa v39, v28 dst_sel:DWORD dst_unused:UNUSED_PAD src0_sel:WORD_1
	v_cvt_f32_f16_e32 v38, v28
	v_cvt_f32_f16_sdwa v37, v29 dst_sel:DWORD dst_unused:UNUSED_PAD src0_sel:WORD_1
	v_cvt_f32_f16_e32 v36, v29
	v_cvt_f32_f16_sdwa v29, v3 dst_sel:DWORD dst_unused:UNUSED_PAD src0_sel:WORD_1
	v_cvt_f32_f16_e32 v28, v3
	v_cvt_f32_f16_sdwa v3, v4 dst_sel:DWORD dst_unused:UNUSED_PAD src0_sel:WORD_1
	v_cvt_f32_f16_e32 v2, v4
	v_cvt_f32_f16_e32 v42, v5
	v_pk_add_f32 v[4:5], v[104:105], v[26:27] neg_lo:[0,1] neg_hi:[0,1]
	s_nop 0
	v_pk_fma_f32 v[4:5], v[4:5], v[18:19], v[26:27]
	v_pk_add_f32 v[18:19], v[114:115], v[26:27] neg_lo:[0,1] neg_hi:[0,1]
	s_nop 0
	v_pk_fma_f32 v[4:5], v[18:19], v[14:15], v[4:5]
	v_pk_add_f32 v[14:15], v[108:109], v[28:29] neg_lo:[0,1] neg_hi:[0,1]
	v_pk_add_f32 v[18:19], v[112:113], v[28:29] neg_lo:[0,1] neg_hi:[0,1]
	v_pk_fma_f32 v[14:15], v[14:15], v[20:21], v[28:29]
	s_nop 0
	v_pk_fma_f32 v[14:15], v[18:19], v[16:17], v[14:15]
	v_pk_add_f32 v[16:17], v[106:107], v[2:3] neg_lo:[0,1] neg_hi:[0,1]
	s_nop 0
	v_pk_fma_f32 v[6:7], v[16:17], v[6:7], v[2:3]
	v_pk_add_f32 v[2:3], v[110:111], v[2:3] neg_lo:[0,1] neg_hi:[0,1]
	s_nop 0
	v_pk_fma_f32 v[6:7], v[2:3], v[10:11], v[6:7]
	v_pk_add_f32 v[2:3], v[102:103], v[42:43] neg_lo:[0,1] neg_hi:[0,1]
	v_pk_mul_f32 v[10:11], v[4:5], v[44:45]
	v_pk_fma_f32 v[2:3], v[2:3], v[8:9], v[42:43]
	v_pk_add_f32 v[8:9], v[96:97], v[42:43] neg_lo:[0,1] neg_hi:[0,1]
	v_pk_mul_f32 v[6:7], v[6:7], v[30:31]
	v_pk_fma_f32 v[8:9], v[8:9], v[12:13], v[2:3]
	s_waitcnt lgkmcnt(0)
	v_add_f32_e32 v2, v71, v136
	v_fmamk_f32 v2, v2, 0x3c800000, v213
	v_cmp_gt_f32_e32 vcc, s27, v2
	v_mul_f32_e32 v3, 0x4b800000, v2
	s_nop 0
	v_cndmask_b32_e32 v2, v2, v3, vcc
	v_rsq_f32_e32 v12, v2
	v_mov_b32_e32 v2, v178
	v_mov_b32_e32 v3, v179
	v_mov_b32_e32 v4, v180
	v_mov_b32_e32 v5, v181
	v_mov_b32_e32 v16, v182
	v_mov_b32_e32 v17, v183
	v_mov_b32_e32 v18, v184
	v_mov_b32_e32 v19, v185
	v_mul_f32_e32 v13, 0x45800000, v12
	v_cndmask_b32_e32 v42, v12, v13, vcc
	v_pk_mul_f32 v[82:83], v[82:83], v[42:43] op_sel_hi:[1,0]
	s_waitcnt vmcnt(2)
	v_pk_mul_f32 v[2:3], v[6:7], v[2:3]
	s_waitcnt vmcnt(2)
	v_pk_mul_f32 v[10:11], v[10:11], v[16:17]
	s_nop 0
	v_add_f32_e32 v10, 0, v10
	v_add_f32_e32 v16, v10, v11
	v_pk_mul_f32 v[10:11], v[14:15], v[24:25]
	s_nop 0
	v_pk_mul_f32 v[10:11], v[10:11], v[18:19]
	s_nop 0
	v_add_f32_e32 v10, v16, v10
	v_add_f32_e32 v10, v10, v11
	v_add_f32_e32 v2, v10, v2
	v_add_f32_e32 v6, v2, v3
	v_pk_mul_f32 v[2:3], v[8:9], v[32:33]
	v_pk_add_f32 v[10:11], v[98:99], v[22:23] neg_lo:[0,1] neg_hi:[0,1]
	v_pk_mul_f32 v[2:3], v[2:3], v[4:5]
	s_nop 0
	v_add_f32_e32 v2, v6, v2
	v_add_f32_e32 v2, v2, v3
	ds_bpermute_b32 v3, v35, v2
	s_waitcnt lgkmcnt(0)
	v_add_f32_e32 v2, v2, v3
	ds_bpermute_b32 v3, v63, v2
	s_waitcnt lgkmcnt(0)
	v_add_f32_e32 v2, v2, v3
	ds_bpermute_b32 v3, v65, v2
	s_waitcnt lgkmcnt(0)
	v_add_f32_e32 v44, v2, v3
	v_lshlrev_b64 v[2:3], 10, v[48:49]
	v_lshl_add_u64 v[2:3], v[56:57], 0, v[2:3]
	v_mov_b32_e32 v2, v174
	v_mov_b32_e32 v3, v175
	v_mov_b32_e32 v4, v176
	v_mov_b32_e32 v5, v177
	s_nop 0
	v_mov_b32_e32 v6, v186
	v_mov_b32_e32 v7, v187
	v_mov_b32_e32 v8, v188
	v_mov_b32_e32 v9, v189
	v_mov_b32_e32 v12, v190
	v_mov_b32_e32 v13, v191
	v_mov_b32_e32 v14, v192
	v_mov_b32_e32 v15, v193
	v_add_u32_e32 v48, s24, v48
	v_cmp_lt_i32_e32 vcc, s75, v48
	s_or_b64 s[40:41], vcc, s[40:41]
	s_waitcnt vmcnt(2)
	v_cvt_f32_f16_e32 v96, v2
	v_cvt_f32_f16_sdwa v97, v2 dst_sel:DWORD dst_unused:UNUSED_PAD src0_sel:WORD_1
	s_waitcnt vmcnt(2)
	v_pk_fma_f32 v[16:17], v[10:11], v[12:13], v[22:23]
	v_mov_b32_e32 v10, v194
	v_mov_b32_e32 v11, v195
	v_mov_b32_e32 v12, v196
	v_mov_b32_e32 v13, v197
	v_mov_b32_e32 v18, v198
	v_mov_b32_e32 v19, v199
	v_mov_b32_e32 v20, v200
	v_mov_b32_e32 v21, v201
	v_pk_add_f32 v[22:23], v[100:101], v[22:23] neg_lo:[0,1] neg_hi:[0,1]
	v_cvt_f32_f16_e32 v2, v3
	v_cvt_f32_f16_sdwa v3, v3 dst_sel:DWORD dst_unused:UNUSED_PAD src0_sel:WORD_1
	s_waitcnt vmcnt(2)
	v_pk_fma_f32 v[46:47], v[22:23], v[18:19], v[16:17]
	v_mov_b32_e32 v16, v202
	v_mov_b32_e32 v17, v203
	v_mov_b32_e32 v18, v204
	v_mov_b32_e32 v19, v205
	v_mov_b32_e32 v26, v206
	v_mov_b32_e32 v27, v207
	v_mov_b32_e32 v28, v208
	v_mov_b32_e32 v29, v209
	v_mov_b32_e32 v22, v226
	v_mov_b32_e32 v23, v227
	v_mov_b32_e32 v24, v228
	v_mov_b32_e32 v25, v229
	v_mov_b32_e32 v30, v230
	v_mov_b32_e32 v31, v231
	v_mov_b32_e32 v32, v232
	v_mov_b32_e32 v33, v233
	s_waitcnt vmcnt(2)
	v_pk_fma_f32 v[26:27], v[82:83], v[26:27], v[30:31]
	v_pk_add_f32 v[30:31], v[90:91], v[40:41] neg_lo:[0,1] neg_hi:[0,1]
	v_pk_fma_f32 v[26:27], v[46:47], v[44:45], v[26:27] op_sel_hi:[1,0,1]
	v_pk_fma_f32 v[14:15], v[30:31], v[14:15], v[40:41]
	v_pk_add_f32 v[30:31], v[94:95], v[40:41] neg_lo:[0,1] neg_hi:[0,1]
	v_pk_mul_f32 v[26:27], v[26:27], v[96:97]
	v_pk_fma_f32 v[14:15], v[30:31], v[20:21], v[14:15]
	v_pk_mul_f32 v[20:21], v[80:81], v[42:43] op_sel_hi:[1,0]
	s_nop 0
	v_pk_fma_f32 v[20:21], v[20:21], v[28:29], v[32:33]
	s_nop 0
	v_pk_fma_f32 v[14:15], v[14:15], v[44:45], v[20:21] op_sel_hi:[1,0,1]
	s_nop 0
	v_pk_mul_f32 v[14:15], v[14:15], v[2:3]
	v_pk_add_f32 v[2:3], v[88:89], v[38:39] neg_lo:[0,1] neg_hi:[0,1]
	s_nop 0
	v_pk_fma_f32 v[2:3], v[2:3], v[6:7], v[38:39]
	v_pk_add_f32 v[6:7], v[92:93], v[38:39] neg_lo:[0,1] neg_hi:[0,1]
	s_nop 0
	v_pk_fma_f32 v[2:3], v[6:7], v[10:11], v[2:3]
	v_cvt_f32_f16_e32 v6, v4
	v_cvt_f32_f16_sdwa v7, v4 dst_sel:DWORD dst_unused:UNUSED_PAD src0_sel:WORD_1
	v_pk_mul_f32 v[10:11], v[78:79], v[42:43] op_sel_hi:[1,0]
	v_cvt_f32_f16_e32 v4, v5
	v_pk_fma_f32 v[10:11], v[10:11], v[16:17], v[22:23]
	v_cvt_f32_f16_sdwa v5, v5 dst_sel:DWORD dst_unused:UNUSED_PAD src0_sel:WORD_1
	v_pk_fma_f32 v[2:3], v[2:3], v[44:45], v[10:11] op_sel_hi:[1,0,1]
	s_nop 0
	v_pk_mul_f32 v[6:7], v[2:3], v[6:7]
	v_pk_add_f32 v[2:3], v[86:87], v[36:37] neg_lo:[0,1] neg_hi:[0,1]
	s_nop 0
	v_pk_fma_f32 v[2:3], v[2:3], v[8:9], v[36:37]
	v_pk_add_f32 v[8:9], v[84:85], v[36:37] neg_lo:[0,1] neg_hi:[0,1]
	s_nop 0
	v_pk_fma_f32 v[2:3], v[8:9], v[12:13], v[2:3]
	v_pk_mul_f32 v[8:9], v[76:77], v[42:43] op_sel_hi:[1,0]
	s_nop 0
	v_pk_fma_f32 v[8:9], v[8:9], v[18:19], v[24:25]
	s_nop 0
	v_pk_fma_f32 v[2:3], v[2:3], v[44:45], v[8:9] op_sel_hi:[1,0,1]
	s_nop 0
	v_pk_mul_f32 v[8:9], v[2:3], v[4:5]
	v_cvt_pk_f16_f32 v2, v26, v27
	v_cvt_pk_f16_f32 v3, v14, v15
	v_cvt_pk_f16_f32 v4, v6, v7
	v_cvt_pk_f16_f32 v5, v8, v9
	global_store_dwordx4 v[74:75], v[2:5], off
	s_andn2_b64 exec, exec, s[40:41]
	s_cbranch_execz .LBB0_297
.LBB0_285:
	v_mov_b64_e32 v[2:3], s[30:31]
	v_mad_i64_i32 v[26:27], s[38:39], v48, s89, v[2:3]
	v_mov_b32_e32 v71, v34
	v_lshl_add_u64 v[74:75], v[26:27], 0, v[70:71]
	s_waitcnt vmcnt(1)
	v_mov_b32_e32 v2, v234
	v_mov_b32_e32 v3, v235
	v_mov_b32_e32 v4, v236
	v_mov_b32_e32 v5, v237
	v_mov_b32_e32 v6, v238
	v_mov_b32_e32 v7, v239
	v_mov_b32_e32 v8, v240
	v_mov_b32_e32 v9, v241
	v_and_b32_e32 v142, 0x7ff, v48
	v_cmp_ne_u32_e32 vcc, 0, v142
	v_mov_b32_e32 v143, 0x1000
	v_mov_b32_e32 v172, 0xfffff100
	v_cndmask_b32_e32 v144, v143, v172, vcc
	v_cndmask_b32_e64 v145, 0, -1, vcc
	s_movk_i32 s100, 0x7ff
	v_lshl_add_u64 v[144:145], v[74:75], 0, v[144:145]
	v_cmp_ne_u32_e32 vcc, s100, v142
	v_mov_b32_e32 v172, 0x2f00
	v_mov_b32_e32 v147, 0
	v_cndmask_b32_e32 v146, v143, v172, vcc
	v_ashrrev_i32_e32 v173, 31, v48
	v_mov_b32_e32 v172, v48
	v_lshl_add_u64 v[146:147], v[74:75], 0, v[146:147]
	v_lshlrev_b64 v[172:173], 10, v[172:173]
	global_load_dwordx4 v[148:151], v[144:145], off
	global_load_dwordx4 v[152:155], v[144:145], off offset:1024
	global_load_dwordx4 v[156:159], v[144:145], off offset:2048
	v_lshl_add_u64 v[172:173], v[56:57], 0, v[172:173]
	global_load_dwordx4 v[160:163], v[146:147], off
	global_load_dwordx4 v[164:167], v[146:147], off offset:1024
	global_load_dwordx4 v[168:171], v[146:147], off offset:2048
	global_load_dwordx4 v[174:177], v[172:173], off
	v_mov_b32_e32 v73, v34
	v_mov_b32_e32 v96, 0
	v_mov_b32_e32 v102, 0
	v_mov_b32_e32 v103, 0
	v_mov_b32_e32 v104, 0
	v_mov_b32_e32 v105, 0
	v_mov_b32_e32 v108, 0
	v_mov_b32_e32 v109, 0
	v_mov_b32_e32 v106, 0
	v_mov_b32_e32 v107, 0
	s_waitcnt vmcnt(8)
	v_cvt_f32_f16_e32 v10, v5
	v_cvt_f32_f16_sdwa v11, v5 dst_sel:DWORD dst_unused:UNUSED_PAD src0_sel:WORD_1
	s_waitcnt vmcnt(8)
	v_cvt_f32_f16_e32 v12, v9
	v_cvt_f32_f16_sdwa v13, v9 dst_sel:DWORD dst_unused:UNUSED_PAD src0_sel:WORD_1
	v_cvt_f32_f16_sdwa v5, v8 dst_sel:DWORD dst_unused:UNUSED_PAD src0_sel:WORD_1
	v_cvt_f32_f16_sdwa v9, v3 dst_sel:DWORD dst_unused:UNUSED_PAD src0_sel:WORD_1
	v_pk_add_f32 v[10:11], v[10:11], v[12:13]
	v_cvt_f32_f16_e32 v12, v4
	v_cvt_f32_f16_sdwa v13, v4 dst_sel:DWORD dst_unused:UNUSED_PAD src0_sel:WORD_1
	v_cvt_f32_f16_e32 v4, v8
	v_cvt_f32_f16_e32 v8, v3
	v_cvt_f32_f16_sdwa v3, v6 dst_sel:DWORD dst_unused:UNUSED_PAD src0_sel:WORD_1
	v_pk_add_f32 v[4:5], v[12:13], v[4:5]
	v_cvt_f32_f16_e32 v12, v7
	v_cvt_f32_f16_sdwa v13, v7 dst_sel:DWORD dst_unused:UNUSED_PAD src0_sel:WORD_1
	v_pk_add_f32 v[8:9], v[8:9], v[12:13]
	v_cvt_f32_f16_e32 v12, v2
	v_cvt_f32_f16_sdwa v13, v2 dst_sel:DWORD dst_unused:UNUSED_PAD src0_sel:WORD_1
	v_cvt_f32_f16_e32 v2, v6
	v_pk_add_f32 v[2:3], v[12:13], v[2:3]
	s_nop 0
	v_add_f32_e32 v6, 0, v2
	v_add_f32_e32 v6, v3, v6
	v_add_f32_e32 v6, v8, v6
	v_add_f32_e32 v6, v9, v6
	v_add_f32_e32 v6, v4, v6
	v_add_f32_e32 v6, v5, v6
	v_add_f32_e32 v6, v10, v6
	v_add_f32_e32 v6, v11, v6
	ds_bpermute_b32 v7, v35, v6
	s_waitcnt lgkmcnt(0)
	v_add_f32_e32 v6, v6, v7
	ds_bpermute_b32 v7, v63, v6
	s_waitcnt lgkmcnt(0)
	v_add_f32_e32 v6, v6, v7
	ds_bpermute_b32 v7, v65, v6
	s_waitcnt lgkmcnt(0)
	v_add_f32_e32 v6, v6, v7
	v_mul_f32_e32 v6, 0x3c800000, v6
	v_pk_add_f32 v[82:83], v[2:3], v[6:7] op_sel_hi:[1,0] neg_lo:[0,1] neg_hi:[0,1]
	v_pk_add_f32 v[80:81], v[8:9], v[6:7] op_sel_hi:[1,0] neg_lo:[0,1] neg_hi:[0,1]
	v_pk_mul_f32 v[2:3], v[82:83], v[82:83]
	v_pk_mul_f32 v[8:9], v[80:81], v[80:81]
	v_add_f32_e32 v2, v2, v3
	v_pk_add_f32 v[78:79], v[4:5], v[6:7] op_sel_hi:[1,0] neg_lo:[0,1] neg_hi:[0,1]
	v_add_f32_e32 v2, v8, v2
	v_pk_mul_f32 v[4:5], v[78:79], v[78:79]
	v_add_f32_e32 v2, v9, v2
	v_pk_add_f32 v[76:77], v[10:11], v[6:7] op_sel_hi:[1,0] neg_lo:[0,1] neg_hi:[0,1]
	v_add_f32_e32 v2, v4, v2
	v_pk_mul_f32 v[6:7], v[76:77], v[76:77]
	v_add_f32_e32 v2, v5, v2
	v_add_f32_e32 v2, v6, v2
	v_add_f32_e32 v2, v7, v2
	ds_bpermute_b32 v3, v35, v2
	v_and_b32_e32 v6, 0x7ff, v48
	v_cmp_ne_u32_e32 vcc, 0, v6
	s_waitcnt lgkmcnt(0)
	v_add_f32_e32 v2, v2, v3
	ds_bpermute_b32 v3, v63, v2
	s_waitcnt lgkmcnt(0)
	v_add_f32_e32 v71, v2, v3
	v_lshl_add_u64 v[2:3], v[26:27], 0, v[72:73]
	global_load_dwordx4 v[2:5], v[2:3], off
	ds_bpermute_b32 v136, v65, v71
	s_and_saveexec_b64 s[38:39], vcc
	s_cbranch_execz .LBB0_287
	s_waitcnt vmcnt(1)
	v_cvt_f32_f16_sdwa v105, v148 dst_sel:DWORD dst_unused:UNUSED_PAD src0_sel:WORD_1
	v_cvt_f32_f16_e32 v104, v148
	v_cvt_f32_f16_sdwa v109, v149 dst_sel:DWORD dst_unused:UNUSED_PAD src0_sel:WORD_1
	v_cvt_f32_f16_e32 v108, v149
	v_cvt_f32_f16_sdwa v107, v150 dst_sel:DWORD dst_unused:UNUSED_PAD src0_sel:WORD_1
	v_cvt_f32_f16_e32 v106, v150
	v_cvt_f32_f16_sdwa v103, v151 dst_sel:DWORD dst_unused:UNUSED_PAD src0_sel:WORD_1
	v_cvt_f32_f16_e32 v102, v151
